# differential loop: s_setprio 1 around role A's MFMA block as well as role B's (role B no longer has a tail)
# speedup vs baseline: 1.0033x; 1.0033x over previous
; __device__ __forceinline__ s16x4 vtr(ldsp p) { return __builtin_bit_cast(s16x4, __builtin_amdgcn_ds_read_tr16_b64_v4i16((LAS v4i16_t*)p)); }
; template <bool DIFF>
; __device__ __forceinline__ void attn_unit(const AttnP& A, int b, int h, int qi, ldsp lds) {
;     ...
;             QK_BLOCK();
;             s16x4 vlo[8], vhi[8];
; #pragma unroll
;             for (int t = 0; t < 2; ++t)
; #pragma unroll
;                 for (int j = 0; j < 4; ++j) { vlo[t * 4 + j] = vtr(Vb + trb + (16 * j) * VP + t * 64); vhi[t * 4 + j] = vtr(Vb + trb + (16 * j + 8) * VP + t * 64); }
;             __builtin_amdgcn_sched_barrier(0);
;             MASK_BLOCK();
;             bool full = (kt == kt0);
;             float psa, psb;
;             if (!full) {
;                 EXPSUM_BLOCK();
;                 if (__any(psa + psb > 1.0e18f)) { full = true; QK_BLOCK();
;     ...
;             __builtin_amdgcn_s_setprio(1);
; #pragma unroll
;             for (int t = 0; t < 2; ++t)
; #pragma unroll
;                 for (int j = 0; j < 4; ++j) {
;                     const bf16x8 vf = (bf16x8){vlo[t * 4 + j][0], vlo[t * 4 + j][1], vlo[t * 4 + j][2], vlo[t * 4 + j][3], vhi[t * 4 + j][0], vhi[t * 4 + j][1], vhi[t * 4 + j][2], vhi[t * 4 + j][3]};
;                     o[t] = __builtin_amdgcn_mfma_f32_32x32x16_bf16(vf, pw[j], o[t], 0, 0, 0);
;                 }
;             if (DIFF) {
; #pragma unroll
;                 for (int t = 2; t < NTD; ++t)
; #pragma unroll
;                     for (int j = 0; j < 4; ++j) { vlo[(t - 2) * 4 + j] = vtr(Vb + trb + (16 * j) * VP + t * 64); vhi[(t - 2) * 4 + j] = vtr(Vb + trb + (16 * j + 8) * VP + t * 64); }
;                 __builtin_amdgcn_sched_barrier(0);
; #pragma unroll
;                 for (int t = 2; t < NTD; ++t)
; #pragma unroll
;                     for (int j = 0; j < 4; ++j) {
;                         const int i = (t - 2) * 4 + j;
;                         const bf16x8 vf = (bf16x8){vlo[i][0], vlo[i][1], vlo[i][2], vlo[i][3], vhi[i][0], vhi[i][1], vhi[i][2], vhi[i][3]};
;                         o[t] = __builtin_amdgcn_mfma_f32_32x32x16_bf16(vf, pw[j], o[t], 0, 0, 0);
;                     }
;             }
;             __builtin_amdgcn_s_setprio(0);
.Lda_s_even:
	ds_read_b64_tr_b16 v[148:149], v252 offset:17472
	ds_read_b64_tr_b16 v[150:151], v252 offset:20032
	ds_read_b64_tr_b16 v[152:153], v252 offset:17408
	ds_read_b64_tr_b16 v[154:155], v252 offset:19968
	ds_read_b64_tr_b16 v[156:157], v252 offset:22592
	ds_read_b64_tr_b16 v[158:159], v252 offset:25152
	ds_read_b64_tr_b16 v[160:161], v252 offset:22528
	ds_read_b64_tr_b16 v[162:163], v252 offset:25088
	ds_read_b64_tr_b16 v[164:165], v252 offset:27712
	ds_read_b64_tr_b16 v[166:167], v252 offset:30272
	ds_read_b64_tr_b16 v[168:169], v252 offset:27648
	ds_read_b64_tr_b16 v[170:171], v252 offset:30208
	ds_read_b64_tr_b16 v[172:173], v252 offset:32768
	ds_read_b64_tr_b16 v[174:175], v252 offset:35328
	ds_read_b64_tr_b16 v[176:177], v252 offset:32832
	ds_read_b64_tr_b16 v[178:179], v252 offset:35392
	s_setprio 1
	s_waitcnt lgkmcnt(14)
	v_mfma_f32_32x32x16_bf16 v[34:49], v[148:151], v[98:101], v[34:49]
	ds_read_b64_tr_b16 v[90:91], v252 offset:17536
	ds_read_b64_tr_b16 v[92:93], v252 offset:20096
	s_waitcnt lgkmcnt(14)
	v_mfma_f32_32x32x16_bf16 v[50:65], v[152:155], v[98:101], v[50:65]
	ds_read_b64_tr_b16 v[94:95], v252 offset:17600
	ds_read_b64_tr_b16 v[96:97], v252 offset:20160
	s_waitcnt lgkmcnt(14)
	v_mfma_f32_32x32x16_bf16 v[34:49], v[156:159], v[102:105], v[34:49]
	ds_read_b64_tr_b16 v[106:107], v252 offset:22656
	ds_read_b64_tr_b16 v[108:109], v252 offset:25216
	s_waitcnt lgkmcnt(14)
	v_mfma_f32_32x32x16_bf16 v[50:65], v[160:163], v[102:105], v[50:65]
	ds_read_b64_tr_b16 v[110:111], v252 offset:22720
	ds_read_b64_tr_b16 v[112:113], v252 offset:25280
	s_waitcnt lgkmcnt(14)
	v_mfma_f32_32x32x16_bf16 v[34:49], v[164:167], v[82:85], v[34:49]
	ds_read_b64_tr_b16 v[240:241], v252 offset:27776
	ds_read_b64_tr_b16 v[242:243], v252 offset:30336
	s_waitcnt lgkmcnt(14)
	v_mfma_f32_32x32x16_bf16 v[50:65], v[168:171], v[82:85], v[50:65]
	ds_read_b64_tr_b16 v[148:149], v252 offset:27840
	ds_read_b64_tr_b16 v[150:151], v252 offset:30400
	s_waitcnt lgkmcnt(14)
	v_mfma_f32_32x32x16_bf16 v[50:65], v[172:175], v[86:89], v[50:65]
	ds_read_b64_tr_b16 v[152:153], v252 offset:32896
	ds_read_b64_tr_b16 v[154:155], v252 offset:35456
	s_waitcnt lgkmcnt(14)
	v_mfma_f32_32x32x16_bf16 v[34:49], v[176:179], v[86:89], v[34:49]
	ds_read_b64_tr_b16 v[156:157], v252 offset:32960
	ds_read_b64_tr_b16 v[158:159], v252 offset:35520
	s_waitcnt lgkmcnt(14)
	v_mfma_f32_32x32x16_bf16 v[18:33], v[90:93], v[98:101], v[18:33]
	ds_read_b128 v[160:163], v234
	s_waitcnt lgkmcnt(13)
	v_mfma_f32_32x32x16_bf16 v[2:17], v[94:97], v[98:101], v[2:17]
	ds_read_b128 v[164:167], v234 offset:8704
	s_waitcnt lgkmcnt(12)
	v_mfma_f32_32x32x16_bf16 v[18:33], v[106:109], v[102:105], v[18:33]
	ds_read_b128 v[168:171], v234 offset:32
	s_waitcnt lgkmcnt(11)
	v_mfma_f32_32x32x16_bf16 v[2:17], v[110:113], v[102:105], v[2:17]
	ds_read_b128 v[172:175], v234 offset:8736
	s_waitcnt lgkmcnt(10)
	v_mfma_f32_32x32x16_bf16 v[18:33], v[240:243], v[82:85], v[18:33]
	ds_read_b128 v[176:179], v234 offset:64
	s_waitcnt lgkmcnt(9)
	v_mfma_f32_32x32x16_bf16 v[2:17], v[148:151], v[82:85], v[2:17]
	ds_read_b128 v[240:243], v234 offset:8768
	s_waitcnt lgkmcnt(8)
	v_mfma_f32_32x32x16_bf16 v[18:33], v[152:155], v[86:89], v[18:33]
	ds_read_b128 v[148:151], v234 offset:96
	s_waitcnt lgkmcnt(7)
	v_mfma_f32_32x32x16_bf16 v[2:17], v[156:159], v[86:89], v[2:17]
	ds_read_b128 v[152:155], v234 offset:8800
	s_waitcnt lgkmcnt(7)
	v_mfma_f32_32x32x16_bf16 v[98:113], v[160:163], v[116:119], v[66:81]
	s_waitcnt lgkmcnt(6)
	v_mfma_f32_32x32x16_bf16 v[82:97], v[164:167], v[116:119], v[66:81]
	s_waitcnt lgkmcnt(5)
	v_mfma_f32_32x32x16_bf16 v[98:113], v[168:171], v[120:123], v[98:113]
	s_waitcnt lgkmcnt(4)
	v_mfma_f32_32x32x16_bf16 v[82:97], v[172:175], v[120:123], v[82:97]
	s_waitcnt lgkmcnt(3)
	v_mfma_f32_32x32x16_bf16 v[98:113], v[176:179], v[124:127], v[98:113]
	s_waitcnt lgkmcnt(2)
	v_mfma_f32_32x32x16_bf16 v[82:97], v[240:243], v[124:127], v[82:97]
	s_waitcnt lgkmcnt(1)
	v_mfma_f32_32x32x16_bf16 v[98:113], v[148:151], v[128:131], v[98:113]
	s_waitcnt lgkmcnt(0)
	v_mfma_f32_32x32x16_bf16 v[82:97], v[152:155], v[128:131], v[82:97]
	s_setprio 0
	s_nop 7
	s_nop 3
	v_exp_f32_e32 v148, v98
	v_exp_f32_e32 v164, v82
	v_exp_f32_e32 v149, v99
	v_exp_f32_e32 v165, v83
	v_add_f32_e32 v237, 0, v148
	v_add_f32_e32 v238, 0, v164
	v_exp_f32_e32 v150, v100
	v_exp_f32_e32 v166, v84
	v_add_f32_e32 v237, v149, v237
	v_add_f32_e32 v238, v165, v238
	v_exp_f32_e32 v151, v101
	v_exp_f32_e32 v167, v85
	v_add_f32_e32 v237, v150, v237
	v_add_f32_e32 v238, v166, v238
	v_exp_f32_e32 v152, v102
	v_exp_f32_e32 v168, v86
	v_add_f32_e32 v237, v151, v237
	v_add_f32_e32 v238, v167, v238
	v_exp_f32_e32 v153, v103
	v_exp_f32_e32 v169, v87
	v_add_f32_e32 v237, v152, v237
	v_add_f32_e32 v238, v168, v238
	v_exp_f32_e32 v154, v104
	v_exp_f32_e32 v170, v88
	v_add_f32_e32 v237, v153, v237
	v_add_f32_e32 v238, v169, v238
	v_exp_f32_e32 v155, v105
	v_exp_f32_e32 v171, v89
	v_add_f32_e32 v237, v154, v237
	v_add_f32_e32 v238, v170, v238
	v_exp_f32_e32 v156, v106
	v_exp_f32_e32 v172, v90
	v_add_f32_e32 v237, v155, v237
	v_add_f32_e32 v238, v171, v238
	v_exp_f32_e32 v157, v107
	v_exp_f32_e32 v173, v91
	v_add_f32_e32 v237, v156, v237
	v_add_f32_e32 v238, v172, v238
	v_exp_f32_e32 v158, v108
	v_exp_f32_e32 v174, v92
	v_add_f32_e32 v237, v157, v237
	v_add_f32_e32 v238, v173, v238
	v_exp_f32_e32 v159, v109
	v_exp_f32_e32 v175, v93
	v_add_f32_e32 v237, v158, v237
	v_add_f32_e32 v238, v174, v238
	v_exp_f32_e32 v160, v110
	v_exp_f32_e32 v176, v94
	v_add_f32_e32 v237, v159, v237
	v_add_f32_e32 v238, v175, v238
	v_exp_f32_e32 v161, v111
	v_exp_f32_e32 v177, v95
	v_add_f32_e32 v237, v160, v237
	v_add_f32_e32 v238, v176, v238
	v_exp_f32_e32 v162, v112
	v_exp_f32_e32 v178, v96
	v_add_f32_e32 v237, v161, v237
	v_add_f32_e32 v238, v177, v238
	v_exp_f32_e32 v163, v113
	v_exp_f32_e32 v179, v97
	v_add_f32_e32 v237, v162, v237
	v_add_f32_e32 v238, v178, v238
	s_nop 0
	v_add_f32_e32 v237, v163, v237
	v_add_f32_e32 v238, v179, v238
	v_add_f32_e32 v204, v237, v238
	v_cmp_lt_f32_e32 vcc, s85, v204
	s_cbranch_vccnz .Lda_s_slow
; __device__ __forceinline__ unsigned cvtpk(float lo, float hi) { f32x2 v = {lo, hi}; bf16x2_t b = __builtin_convertvector(v, bf16x2_t); return __builtin_bit_cast(unsigned, b); }
; template <bool DIFF>
; __device__ __forceinline__ void attn_unit(const AttnP& A, int b, int h, int qi, ldsp lds) {
;     ...
;             l_run += psa + psb;
;     ...
;             bf16x8 pw[4];
; #pragma unroll
;             for (int j = 0; j < 4; ++j) {
;                 u32x4 pk;
;                 if (j < 2) { const int rb = 8 * (j & 1); pk.x = cvtpk(s0[rb], s0[rb + 1]); pk.y = cvtpk(s0[rb + 2], s0[rb + 3]); pk.z = cvtpk(s0[rb + 4], s0[rb + 5]); pk.w = cvtpk(s0[rb + 6], s0[rb + 7]); }
;                 else { const int rb = 8 * (j & 1); pk.x = cvtpk(s1[rb], s1[rb + 1]); pk.y = cvtpk(s1[rb + 2], s1[rb + 3]); pk.z = cvtpk(s1[rb + 4], s1[rb + 5]); pk.w = cvtpk(s1[rb + 6], s1[rb + 7]); }
;                 pw[j] = __builtin_bit_cast(bf16x8, pk);
;             }
;             __builtin_amdgcn_sched_barrier(0);
;             __builtin_amdgcn_s_setprio(1);
; #pragma unroll
;             for (int t = 0; t < 2; ++t)
; #pragma unroll
;                 for (int j = 0; j < 4; ++j) {
;                     const bf16x8 vf = (bf16x8){vlo[t * 4 + j][0], vlo[t * 4 + j][1], vlo[t * 4 + j][2], vlo[t * 4 + j][3], vhi[t * 4 + j][0], vhi[t * 4 + j][1], vhi[t * 4 + j][2], vhi[t * 4 + j][3]};
;                     o[t] = __builtin_amdgcn_mfma_f32_32x32x16_bf16(vf, pw[j], o[t], 0, 0, 0);
;                 }
;             if (DIFF) {
; #pragma unroll
;                 for (int t = 2; t < NTD; ++t)
; #pragma unroll
;                     for (int j = 0; j < 4; ++j) { vlo[(t - 2) * 4 + j] = vtr(Vb + trb + (16 * j) * VP + t * 64); vhi[(t - 2) * 4 + j] = vtr(Vb + trb + (16 * j + 8) * VP + t * 64); }
;                 __builtin_amdgcn_sched_barrier(0);
; #pragma unroll
;                 for (int t = 2; t < NTD; ++t)
; #pragma unroll
;                     for (int j = 0; j < 4; ++j) {
;                         const int i = (t - 2) * 4 + j;
;                         const bf16x8 vf = (bf16x8){vlo[i][0], vlo[i][1], vlo[i][2], vlo[i][3], vhi[i][0], vhi[i][1], vhi[i][2], vhi[i][3]};
;                         o[t] = __builtin_amdgcn_mfma_f32_32x32x16_bf16(vf, pw[j], o[t], 0, 0, 0);
;                     }
;             }
;             __builtin_amdgcn_s_setprio(0);
;         }
;         if (kt + 1 < nt) STORE_TILE((kt + 1) & 1);
	v_cvt_pk_bf16_f32 v98, v148, v149
	v_cvt_pk_bf16_f32 v99, v150, v151
	v_cvt_pk_bf16_f32 v100, v152, v153
	v_cvt_pk_bf16_f32 v101, v154, v155
	v_cvt_pk_bf16_f32 v102, v156, v157
	v_cvt_pk_bf16_f32 v103, v158, v159
	v_cvt_pk_bf16_f32 v104, v160, v161
	v_cvt_pk_bf16_f32 v105, v162, v163
	v_cvt_pk_bf16_f32 v82, v164, v165
	v_cvt_pk_bf16_f32 v83, v166, v167
	v_cvt_pk_bf16_f32 v84, v168, v169
	v_cvt_pk_bf16_f32 v85, v170, v171
	v_cvt_pk_bf16_f32 v86, v172, v173
	v_cvt_pk_bf16_f32 v87, v174, v175
	v_cvt_pk_bf16_f32 v88, v176, v177
	v_cvt_pk_bf16_f32 v89, v178, v179
	v_add_f32_e32 v230, v204, v230
	s_waitcnt vmcnt(0)
	ds_write_b128 v226, v[132:135] offset:38144
	ds_write_b128 v228, v[140:143] offset:38144
	ds_write_b128 v227, v[136:139] offset:17408
	ds_write_b128 v229, v[144:147] offset:17408
	global_load_dwordx4 v[136:139], v[196:197], off offset:2048
	global_load_dwordx4 v[144:147], v[198:199], off offset:2048
	v_lshl_add_u64 v[196:197], v[196:197], 0, s[26:27]
	v_lshl_add_u64 v[198:199], v[198:199], 0, s[26:27]
	global_load_dwordx4 v[132:135], v[196:197], off offset:1024
	global_load_dwordx4 v[140:143], v[198:199], off offset:1024
	s_waitcnt lgkmcnt(0)
	s_barrier
	s_add_i32 s75, s75, 1
	s_add_i32 s74, s74, 64
	s_cmp_gt_i32 s75, s23
	s_cbranch_scc1 .Lda_gen
.Lda_s_odd:
	ds_read_b64_tr_b16 v[148:149], v231 offset:17472
	ds_read_b64_tr_b16 v[150:151], v231 offset:20032
	ds_read_b64_tr_b16 v[152:153], v231 offset:17408
	ds_read_b64_tr_b16 v[154:155], v231 offset:19968
	ds_read_b64_tr_b16 v[156:157], v231 offset:22592
	ds_read_b64_tr_b16 v[158:159], v231 offset:25152
	ds_read_b64_tr_b16 v[160:161], v231 offset:22528
	ds_read_b64_tr_b16 v[162:163], v231 offset:25088
	ds_read_b64_tr_b16 v[164:165], v231 offset:27712
	ds_read_b64_tr_b16 v[166:167], v231 offset:30272
	ds_read_b64_tr_b16 v[168:169], v231 offset:27648
	ds_read_b64_tr_b16 v[170:171], v231 offset:30208
	ds_read_b64_tr_b16 v[172:173], v231 offset:32768
	ds_read_b64_tr_b16 v[174:175], v231 offset:35328
	ds_read_b64_tr_b16 v[176:177], v231 offset:32832
	ds_read_b64_tr_b16 v[178:179], v231 offset:35392
	s_setprio 1
	s_waitcnt lgkmcnt(14)
	v_mfma_f32_32x32x16_bf16 v[34:49], v[148:151], v[98:101], v[34:49]
	ds_read_b64_tr_b16 v[90:91], v231 offset:17536
	ds_read_b64_tr_b16 v[92:93], v231 offset:20096
	s_waitcnt lgkmcnt(14)
	v_mfma_f32_32x32x16_bf16 v[50:65], v[152:155], v[98:101], v[50:65]
	ds_read_b64_tr_b16 v[94:95], v231 offset:17600
	ds_read_b64_tr_b16 v[96:97], v231 offset:20160
	s_waitcnt lgkmcnt(14)
	v_mfma_f32_32x32x16_bf16 v[34:49], v[156:159], v[102:105], v[34:49]
	ds_read_b64_tr_b16 v[106:107], v231 offset:22656
	ds_read_b64_tr_b16 v[108:109], v231 offset:25216
	s_waitcnt lgkmcnt(14)
	v_mfma_f32_32x32x16_bf16 v[50:65], v[160:163], v[102:105], v[50:65]
	ds_read_b64_tr_b16 v[110:111], v231 offset:22720
	ds_read_b64_tr_b16 v[112:113], v231 offset:25280
	s_waitcnt lgkmcnt(14)
	v_mfma_f32_32x32x16_bf16 v[34:49], v[164:167], v[82:85], v[34:49]
	ds_read_b64_tr_b16 v[240:241], v231 offset:27776
	ds_read_b64_tr_b16 v[242:243], v231 offset:30336
	s_waitcnt lgkmcnt(14)
	v_mfma_f32_32x32x16_bf16 v[50:65], v[168:171], v[82:85], v[50:65]
	ds_read_b64_tr_b16 v[148:149], v231 offset:27840
	ds_read_b64_tr_b16 v[150:151], v231 offset:30400
	s_waitcnt lgkmcnt(14)
	v_mfma_f32_32x32x16_bf16 v[50:65], v[172:175], v[86:89], v[50:65]
	ds_read_b64_tr_b16 v[152:153], v231 offset:32896
	ds_read_b64_tr_b16 v[154:155], v231 offset:35456
	s_waitcnt lgkmcnt(14)
	v_mfma_f32_32x32x16_bf16 v[34:49], v[176:179], v[86:89], v[34:49]
	ds_read_b64_tr_b16 v[156:157], v231 offset:32960
	ds_read_b64_tr_b16 v[158:159], v231 offset:35520
	s_waitcnt lgkmcnt(14)
	v_mfma_f32_32x32x16_bf16 v[18:33], v[90:93], v[98:101], v[18:33]
	ds_read_b128 v[160:163], v234 offset:38144
	s_waitcnt lgkmcnt(13)
	v_mfma_f32_32x32x16_bf16 v[2:17], v[94:97], v[98:101], v[2:17]
	ds_read_b128 v[164:167], v234 offset:46848
	s_waitcnt lgkmcnt(12)
	v_mfma_f32_32x32x16_bf16 v[18:33], v[106:109], v[102:105], v[18:33]
	ds_read_b128 v[168:171], v234 offset:38176
	s_waitcnt lgkmcnt(11)
	v_mfma_f32_32x32x16_bf16 v[2:17], v[110:113], v[102:105], v[2:17]
	ds_read_b128 v[172:175], v234 offset:46880
	s_waitcnt lgkmcnt(10)
	v_mfma_f32_32x32x16_bf16 v[18:33], v[240:243], v[82:85], v[18:33]
	ds_read_b128 v[176:179], v234 offset:38208
	s_waitcnt lgkmcnt(9)
	v_mfma_f32_32x32x16_bf16 v[2:17], v[148:151], v[82:85], v[2:17]
	ds_read_b128 v[240:243], v234 offset:46912
	s_waitcnt lgkmcnt(8)
	v_mfma_f32_32x32x16_bf16 v[18:33], v[152:155], v[86:89], v[18:33]
	ds_read_b128 v[148:151], v234 offset:38240
	s_waitcnt lgkmcnt(7)
	v_mfma_f32_32x32x16_bf16 v[2:17], v[156:159], v[86:89], v[2:17]
	ds_read_b128 v[152:155], v234 offset:46944
	s_waitcnt lgkmcnt(7)
	v_mfma_f32_32x32x16_bf16 v[98:113], v[160:163], v[116:119], v[66:81]
	s_waitcnt lgkmcnt(6)
	v_mfma_f32_32x32x16_bf16 v[82:97], v[164:167], v[116:119], v[66:81]
	s_waitcnt lgkmcnt(5)
	v_mfma_f32_32x32x16_bf16 v[98:113], v[168:171], v[120:123], v[98:113]
	s_waitcnt lgkmcnt(4)
	v_mfma_f32_32x32x16_bf16 v[82:97], v[172:175], v[120:123], v[82:97]
	s_waitcnt lgkmcnt(3)
	v_mfma_f32_32x32x16_bf16 v[98:113], v[176:179], v[124:127], v[98:113]
	s_waitcnt lgkmcnt(2)
	v_mfma_f32_32x32x16_bf16 v[82:97], v[240:243], v[124:127], v[82:97]
	s_waitcnt lgkmcnt(1)
	v_mfma_f32_32x32x16_bf16 v[98:113], v[148:151], v[128:131], v[98:113]
	s_waitcnt lgkmcnt(0)
; __device__ __forceinline__ s16x4 vtr(ldsp p) { return __builtin_bit_cast(s16x4, __builtin_amdgcn_ds_read_tr16_b64_v4i16((LAS v4i16_t*)p)); }
; template <bool DIFF>
; __device__ __forceinline__ void attn_unit(const AttnP& A, int b, int h, int qi, ldsp lds) {
;     ...
;             QK_BLOCK();
;             s16x4 vlo[8], vhi[8];
; #pragma unroll
;             for (int t = 0; t < 2; ++t)
; #pragma unroll
;                 for (int j = 0; j < 4; ++j) { vlo[t * 4 + j] = vtr(Vb + trb + (16 * j) * VP + t * 64); vhi[t * 4 + j] = vtr(Vb + trb + (16 * j + 8) * VP + t * 64); }
;             __builtin_amdgcn_sched_barrier(0);
;             MASK_BLOCK();
;             bool full = (kt == kt0);
;             float psa, psb;
;             if (!full) {
;                 EXPSUM_BLOCK();
;                 if (__any(psa + psb > 1.0e18f)) { full = true; QK_BLOCK();
; #pragma unroll
;                     for (int t = 0; t < 2; ++t)
; #pragma unroll
;                         for (int j = 0; j < 4; ++j) { vlo[t * 4 + j] = vtr(Vb + trb + (16 * j) * VP + t * 64); vhi[t * 4 + j] = vtr(Vb + trb + (16 * j + 8) * VP + t * 64); }
;                     MASK_BLOCK(); }
;             }
;             if (full) {
;                 float ma = fmaxf(fmaxf(s0[0], s0[1]), s1[0]), mb = fmaxf(fmaxf(s0[2], s0[3]), s1[1]);
;                 ma = fmaxf(fmaxf(ma, s1[2]), s1[3]);
; #pragma unroll
;                 for (int r = 4; r < 16; r += 4) { ma = fmaxf(fmaxf(ma, s0[r]), s0[r + 1]); mb = fmaxf(fmaxf(mb, s0[r + 2]), s0[r + 3]); ma = fmaxf(fmaxf(ma, s1[r]), s1[r + 1]); mb = fmaxf(fmaxf(mb, s1[r + 2]), s1[r + 3]); }
;                 const float rm = swap32_max(fmaxf(ma, mb));
;                 const float dl = (kt == kt0) ? ((rm == -INFINITY) ? 0.f : rm) : fmaxf(rm, 0.f);
;                 mhat += dl;
; #pragma unroll
;                 for (int r = 0; r < 16; ++r) { s0[r] -= dl; s1[r] -= dl; negm[r] = -mhat; }
;                 const float f = (kt == kt0) ? 1.0f : __builtin_amdgcn_exp2f(-dl);
;                 l_run *= f;
; #pragma unroll
;                 for (int t = 0; t < NTD; ++t)
; #pragma unroll
;                     for (int r = 0; r < 16; ++r) o[t][r] *= f;
;                 EXPSUM_BLOCK();
;             }
;             l_run += psa + psb;
;     ...
;             bf16x8 pw[4];
; #pragma unroll
;             for (int j = 0; j < 4; ++j) {
;                 u32x4 pk;
	v_mfma_f32_32x32x16_bf16 v[82:97], v[152:155], v[128:131], v[82:97]
	s_setprio 0
	s_nop 7
	s_nop 3
	v_exp_f32_e32 v148, v98
	v_exp_f32_e32 v164, v82
	v_exp_f32_e32 v149, v99
	v_exp_f32_e32 v165, v83
	v_add_f32_e32 v237, 0, v148
	v_add_f32_e32 v238, 0, v164
	v_exp_f32_e32 v150, v100
	v_exp_f32_e32 v166, v84
	v_add_f32_e32 v237, v149, v237
	v_add_f32_e32 v238, v165, v238
	v_exp_f32_e32 v151, v101
	v_exp_f32_e32 v167, v85
	v_add_f32_e32 v237, v150, v237
	v_add_f32_e32 v238, v166, v238
	v_exp_f32_e32 v152, v102
	v_exp_f32_e32 v168, v86
	v_add_f32_e32 v237, v151, v237
	v_add_f32_e32 v238, v167, v238
	v_exp_f32_e32 v153, v103
	v_exp_f32_e32 v169, v87
	v_add_f32_e32 v237, v152, v237
	v_add_f32_e32 v238, v168, v238
	v_exp_f32_e32 v154, v104
	v_exp_f32_e32 v170, v88
	v_add_f32_e32 v237, v153, v237
	v_add_f32_e32 v238, v169, v238
	v_exp_f32_e32 v155, v105
	v_exp_f32_e32 v171, v89
	v_add_f32_e32 v237, v154, v237
	v_add_f32_e32 v238, v170, v238
	v_exp_f32_e32 v156, v106
	v_exp_f32_e32 v172, v90
	v_add_f32_e32 v237, v155, v237
	v_add_f32_e32 v238, v171, v238
	v_exp_f32_e32 v157, v107
	v_exp_f32_e32 v173, v91
	v_add_f32_e32 v237, v156, v237
	v_add_f32_e32 v238, v172, v238
	v_exp_f32_e32 v158, v108
	v_exp_f32_e32 v174, v92
	v_add_f32_e32 v237, v157, v237
	v_add_f32_e32 v238, v173, v238
	v_exp_f32_e32 v159, v109
	v_exp_f32_e32 v175, v93
	v_add_f32_e32 v237, v158, v237
	v_add_f32_e32 v238, v174, v238
	v_exp_f32_e32 v160, v110
	v_exp_f32_e32 v176, v94
	v_add_f32_e32 v237, v159, v237
	v_add_f32_e32 v238, v175, v238
	v_exp_f32_e32 v161, v111
	v_exp_f32_e32 v177, v95
	v_add_f32_e32 v237, v160, v237
	v_add_f32_e32 v238, v176, v238
	v_exp_f32_e32 v162, v112
	v_exp_f32_e32 v178, v96
	v_add_f32_e32 v237, v161, v237
	v_add_f32_e32 v238, v177, v238
	v_exp_f32_e32 v163, v113
	v_exp_f32_e32 v179, v97
	v_add_f32_e32 v237, v162, v237
	v_add_f32_e32 v238, v178, v238
	s_nop 0
	v_add_f32_e32 v237, v163, v237
	v_add_f32_e32 v238, v179, v238
	v_add_f32_e32 v204, v237, v238
	v_cmp_lt_f32_e32 vcc, s85, v204
	s_cbranch_vccnz .Lda_s_slow
	v_cvt_pk_bf16_f32 v98, v148, v149
	v_cvt_pk_bf16_f32 v99, v150, v151
	v_cvt_pk_bf16_f32 v100, v152, v153
	v_cvt_pk_bf16_f32 v101, v154, v155
	v_cvt_pk_bf16_f32 v102, v156, v157
	v_cvt_pk_bf16_f32 v103, v158, v159
	v_cvt_pk_bf16_f32 v104, v160, v161
	v_cvt_pk_bf16_f32 v105, v162, v163
	v_cvt_pk_bf16_f32 v82, v164, v165
	v_cvt_pk_bf16_f32 v83, v166, v167
	v_cvt_pk_bf16_f32 v84, v168, v169
	v_cvt_pk_bf16_f32 v85, v170, v171
	v_cvt_pk_bf16_f32 v86, v172, v173
	v_cvt_pk_bf16_f32 v87, v174, v175
	v_cvt_pk_bf16_f32 v88, v176, v177
	v_cvt_pk_bf16_f32 v89, v178, v179
	v_add_f32_e32 v230, v204, v230
	s_waitcnt vmcnt(0)
	ds_write_b128 v226, v[132:135]
	ds_write_b128 v228, v[140:143]
	ds_write_b128 v227, v[136:139] offset:55552
	ds_write_b128 v229, v[144:147] offset:55552
	global_load_dwordx4 v[136:139], v[196:197], off offset:2048
	global_load_dwordx4 v[144:147], v[198:199], off offset:2048
	v_lshl_add_u64 v[196:197], v[196:197], 0, s[26:27]
	v_lshl_add_u64 v[198:199], v[198:199], 0, s[26:27]
	global_load_dwordx4 v[132:135], v[196:197], off offset:1024
	global_load_dwordx4 v[140:143], v[198:199], off offset:1024
	s_waitcnt lgkmcnt(0)
	s_barrier
	s_add_i32 s75, s75, 1
	s_add_i32 s74, s74, 64
	s_cmp_le_i32 s75, s23
	s_cbranch_scc1 .Lda_s_even
; __device__ __forceinline__ s16x4 vtr(ldsp p) { return __builtin_bit_cast(s16x4, __builtin_amdgcn_ds_read_tr16_b64_v4i16((LAS v4i16_t*)p)); }
; template <bool DIFF>
; __device__ __forceinline__ void attn_unit(const AttnP& A, int b, int h, int qi, ldsp lds) {
;     ...
;             __builtin_amdgcn_s_setprio(1);
; #pragma unroll
;             for (int t = 0; t < 2; ++t)
; #pragma unroll
;                 for (int j = 0; j < 4; ++j) {
;                     const bf16x8 vf = (bf16x8){vlo[t * 4 + j][0], vlo[t * 4 + j][1], vlo[t * 4 + j][2], vlo[t * 4 + j][3], vhi[t * 4 + j][0], vhi[t * 4 + j][1], vhi[t * 4 + j][2], vhi[t * 4 + j][3]};
;                     o[t] = __builtin_amdgcn_mfma_f32_32x32x16_bf16(vf, pw[j], o[t], 0, 0, 0);
;                 }
;             if (DIFF) {
; #pragma unroll
;                 for (int t = 2; t < NTD; ++t)
; #pragma unroll
;                     for (int j = 0; j < 4; ++j) { vlo[(t - 2) * 4 + j] = vtr(Vb + trb + (16 * j) * VP + t * 64); vhi[(t - 2) * 4 + j] = vtr(Vb + trb + (16 * j + 8) * VP + t * 64); }
;                 __builtin_amdgcn_sched_barrier(0);
; #pragma unroll
;                 for (int t = 2; t < NTD; ++t)
; #pragma unroll
;                     for (int j = 0; j < 4; ++j) {
;                         const int i = (t - 2) * 4 + j;
;                         const bf16x8 vf = (bf16x8){vlo[i][0], vlo[i][1], vlo[i][2], vlo[i][3], vhi[i][0], vhi[i][1], vhi[i][2], vhi[i][3]};
;                         o[t] = __builtin_amdgcn_mfma_f32_32x32x16_bf16(vf, pw[j], o[t], 0, 0, 0);
;                     }
;             }
;             __builtin_amdgcn_s_setprio(0);
.Lda_gen:
	s_bitcmp1_b32 s75, 0
	s_cselect_b32 s45, 0x9500, 0
	s_sub_i32 s71, 0x9500, s45
	s_cmp_eq_u32 s75, 0
	s_cbranch_scc1 .Lda_first
	s_cmp_gt_i32 s75, s44
	s_cbranch_scc1 .Lda_idle
	s_cmp_eq_u32 s75, s44
	s_cbranch_scc1 .Lda_last
	v_add_u32_e32 v239, s45, v234
	v_add_u32_e32 v236, s71, v231
	ds_read_b64_tr_b16 v[148:149], v236 offset:17472
	ds_read_b64_tr_b16 v[150:151], v236 offset:20032
	ds_read_b64_tr_b16 v[152:153], v236 offset:17408
	ds_read_b64_tr_b16 v[154:155], v236 offset:19968
	ds_read_b64_tr_b16 v[156:157], v236 offset:22592
	ds_read_b64_tr_b16 v[158:159], v236 offset:25152
	ds_read_b64_tr_b16 v[160:161], v236 offset:22528
	ds_read_b64_tr_b16 v[162:163], v236 offset:25088
	ds_read_b64_tr_b16 v[164:165], v236 offset:27712
	ds_read_b64_tr_b16 v[166:167], v236 offset:30272
	ds_read_b64_tr_b16 v[168:169], v236 offset:27648
	ds_read_b64_tr_b16 v[170:171], v236 offset:30208
	ds_read_b64_tr_b16 v[172:173], v236 offset:32768
	ds_read_b64_tr_b16 v[174:175], v236 offset:35328
	ds_read_b64_tr_b16 v[176:177], v236 offset:32832
	ds_read_b64_tr_b16 v[178:179], v236 offset:35392
	s_setprio 1
	s_waitcnt lgkmcnt(14)
	v_mfma_f32_32x32x16_bf16 v[34:49], v[148:151], v[98:101], v[34:49]
	ds_read_b64_tr_b16 v[90:91], v236 offset:17536
	ds_read_b64_tr_b16 v[92:93], v236 offset:20096
	s_waitcnt lgkmcnt(14)
	v_mfma_f32_32x32x16_bf16 v[50:65], v[152:155], v[98:101], v[50:65]
	ds_read_b64_tr_b16 v[94:95], v236 offset:17600
	ds_read_b64_tr_b16 v[96:97], v236 offset:20160
	s_waitcnt lgkmcnt(14)
	v_mfma_f32_32x32x16_bf16 v[34:49], v[156:159], v[102:105], v[34:49]
	ds_read_b64_tr_b16 v[106:107], v236 offset:22656
	ds_read_b64_tr_b16 v[108:109], v236 offset:25216
	s_waitcnt lgkmcnt(14)
	v_mfma_f32_32x32x16_bf16 v[50:65], v[160:163], v[102:105], v[50:65]
	ds_read_b64_tr_b16 v[110:111], v236 offset:22720
	ds_read_b64_tr_b16 v[112:113], v236 offset:25280
	s_waitcnt lgkmcnt(14)
	v_mfma_f32_32x32x16_bf16 v[34:49], v[164:167], v[82:85], v[34:49]
	ds_read_b64_tr_b16 v[240:241], v236 offset:27776
	ds_read_b64_tr_b16 v[242:243], v236 offset:30336
	s_waitcnt lgkmcnt(14)
	v_mfma_f32_32x32x16_bf16 v[50:65], v[168:171], v[82:85], v[50:65]
	ds_read_b64_tr_b16 v[148:149], v236 offset:27840
	ds_read_b64_tr_b16 v[150:151], v236 offset:30400
	s_waitcnt lgkmcnt(14)
	v_mfma_f32_32x32x16_bf16 v[50:65], v[172:175], v[86:89], v[50:65]
	ds_read_b64_tr_b16 v[152:153], v236 offset:32896
	ds_read_b64_tr_b16 v[154:155], v236 offset:35456
	s_waitcnt lgkmcnt(14)
	v_mfma_f32_32x32x16_bf16 v[34:49], v[176:179], v[86:89], v[34:49]
	ds_read_b64_tr_b16 v[156:157], v236 offset:32960
	ds_read_b64_tr_b16 v[158:159], v236 offset:35520
	s_waitcnt lgkmcnt(14)
	v_mfma_f32_32x32x16_bf16 v[18:33], v[90:93], v[98:101], v[18:33]
	ds_read_b128 v[160:163], v239
	s_waitcnt lgkmcnt(13)
	v_mfma_f32_32x32x16_bf16 v[2:17], v[94:97], v[98:101], v[2:17]
	ds_read_b128 v[164:167], v239 offset:8704
	s_waitcnt lgkmcnt(12)
	v_mfma_f32_32x32x16_bf16 v[18:33], v[106:109], v[102:105], v[18:33]
	ds_read_b128 v[168:171], v239 offset:32
	s_waitcnt lgkmcnt(11)
	v_mfma_f32_32x32x16_bf16 v[2:17], v[110:113], v[102:105], v[2:17]
	ds_read_b128 v[172:175], v239 offset:8736
	s_waitcnt lgkmcnt(10)
	v_mfma_f32_32x32x16_bf16 v[18:33], v[240:243], v[82:85], v[18:33]
	ds_read_b128 v[176:179], v239 offset:64
	s_waitcnt lgkmcnt(9)
	v_mfma_f32_32x32x16_bf16 v[2:17], v[148:151], v[82:85], v[2:17]
	ds_read_b128 v[240:243], v239 offset:8768
	s_waitcnt lgkmcnt(8)
	v_mfma_f32_32x32x16_bf16 v[18:33], v[152:155], v[86:89], v[18:33]
	ds_read_b128 v[148:151], v239 offset:96
	s_waitcnt lgkmcnt(7)
	v_mfma_f32_32x32x16_bf16 v[2:17], v[156:159], v[86:89], v[2:17]
	ds_read_b128 v[152:155], v239 offset:8800
	s_waitcnt lgkmcnt(7)
	v_mfma_f32_32x32x16_bf16 v[98:113], v[160:163], v[116:119], v[66:81]
	s_waitcnt lgkmcnt(6)
	v_mfma_f32_32x32x16_bf16 v[82:97], v[164:167], v[116:119], v[66:81]
	s_waitcnt lgkmcnt(5)
	v_mfma_f32_32x32x16_bf16 v[98:113], v[168:171], v[120:123], v[98:113]
	s_waitcnt lgkmcnt(4)
	v_mfma_f32_32x32x16_bf16 v[82:97], v[172:175], v[120:123], v[82:97]
	s_waitcnt lgkmcnt(3)
	v_mfma_f32_32x32x16_bf16 v[98:113], v[176:179], v[124:127], v[98:113]
	s_waitcnt lgkmcnt(2)
	v_mfma_f32_32x32x16_bf16 v[82:97], v[240:243], v[124:127], v[82:97]
	s_waitcnt lgkmcnt(1)
	v_mfma_f32_32x32x16_bf16 v[98:113], v[148:151], v[128:131], v[98:113]
	s_waitcnt lgkmcnt(0)
	v_mfma_f32_32x32x16_bf16 v[82:97], v[152:155], v[128:131], v[82:97]
	s_setprio 0

; __device__ __forceinline__ s16x4 vtr(ldsp p) { return __builtin_bit_cast(s16x4, __builtin_amdgcn_ds_read_tr16_b64_v4i16((LAS v4i16_t*)p)); }
; template <bool DIFF>
; __device__ __forceinline__ void attn_unit(const AttnP& A, int b, int h, int qi, ldsp lds) {
;     ...
;             __builtin_amdgcn_s_setprio(1);
; #pragma unroll
;             for (int t = 0; t < 2; ++t)
; #pragma unroll
;                 for (int j = 0; j < 4; ++j) {
;                     const bf16x8 vf = (bf16x8){vlo[t * 4 + j][0], vlo[t * 4 + j][1], vlo[t * 4 + j][2], vlo[t * 4 + j][3], vhi[t * 4 + j][0], vhi[t * 4 + j][1], vhi[t * 4 + j][2], vhi[t * 4 + j][3]};
;                     o[t] = __builtin_amdgcn_mfma_f32_32x32x16_bf16(vf, pw[j], o[t], 0, 0, 0);
;                 }
;             if (DIFF) {
; #pragma unroll
;                 for (int t = 2; t < NTD; ++t)
; #pragma unroll
;                     for (int j = 0; j < 4; ++j) { vlo[(t - 2) * 4 + j] = vtr(Vb + trb + (16 * j) * VP + t * 64); vhi[(t - 2) * 4 + j] = vtr(Vb + trb + (16 * j + 8) * VP + t * 64); }
;                 __builtin_amdgcn_sched_barrier(0);
; #pragma unroll
;                 for (int t = 2; t < NTD; ++t)
; #pragma unroll
;                     for (int j = 0; j < 4; ++j) {
;                         const int i = (t - 2) * 4 + j;
;                         const bf16x8 vf = (bf16x8){vlo[i][0], vlo[i][1], vlo[i][2], vlo[i][3], vhi[i][0], vhi[i][1], vhi[i][2], vhi[i][3]};
;                         o[t] = __builtin_amdgcn_mfma_f32_32x32x16_bf16(vf, pw[j], o[t], 0, 0, 0);
;                     }
;             }
;             __builtin_amdgcn_s_setprio(0);
.Lda_first:
	v_add_u32_e32 v239, s45, v234
	ds_read_b128 v[148:151], v239
	ds_read_b128 v[152:155], v239 offset:8704
	ds_read_b128 v[156:159], v239 offset:32
	ds_read_b128 v[160:163], v239 offset:8736
	ds_read_b128 v[164:167], v239 offset:64
	ds_read_b128 v[168:171], v239 offset:8768
	ds_read_b128 v[172:175], v239 offset:96
	ds_read_b128 v[176:179], v239 offset:8800
	s_setprio 1
	s_waitcnt lgkmcnt(7)
	v_mfma_f32_32x32x16_bf16 v[98:113], v[148:151], v[116:119], v[66:81]
	s_waitcnt lgkmcnt(6)
	v_mfma_f32_32x32x16_bf16 v[82:97], v[152:155], v[116:119], v[66:81]
	s_waitcnt lgkmcnt(5)
	v_mfma_f32_32x32x16_bf16 v[98:113], v[156:159], v[120:123], v[98:113]
	s_waitcnt lgkmcnt(4)
	v_mfma_f32_32x32x16_bf16 v[82:97], v[160:163], v[120:123], v[82:97]
	s_waitcnt lgkmcnt(3)
	v_mfma_f32_32x32x16_bf16 v[98:113], v[164:167], v[124:127], v[98:113]
	s_waitcnt lgkmcnt(2)
	v_mfma_f32_32x32x16_bf16 v[82:97], v[168:171], v[124:127], v[82:97]
	s_waitcnt lgkmcnt(1)
	v_mfma_f32_32x32x16_bf16 v[98:113], v[172:175], v[128:131], v[98:113]
	s_waitcnt lgkmcnt(0)
	v_mfma_f32_32x32x16_bf16 v[82:97], v[176:179], v[128:131], v[82:97]
	s_setprio 0
	s_branch .Lda_postqk
.Lda_last:
	v_add_u32_e32 v239, s45, v234
	v_add_u32_e32 v236, s71, v231
	ds_read_b64_tr_b16 v[148:149], v236 offset:17472
	ds_read_b64_tr_b16 v[150:151], v236 offset:20032
	ds_read_b64_tr_b16 v[152:153], v236 offset:17408
	ds_read_b64_tr_b16 v[154:155], v236 offset:19968
	ds_read_b64_tr_b16 v[156:157], v236 offset:22592
	ds_read_b64_tr_b16 v[158:159], v236 offset:25152
	ds_read_b64_tr_b16 v[160:161], v236 offset:22528
	ds_read_b64_tr_b16 v[162:163], v236 offset:25088
	ds_read_b64_tr_b16 v[164:165], v236 offset:27712
	ds_read_b64_tr_b16 v[166:167], v236 offset:30272
	ds_read_b64_tr_b16 v[168:169], v236 offset:27648
	ds_read_b64_tr_b16 v[170:171], v236 offset:30208
	ds_read_b64_tr_b16 v[172:173], v236 offset:32768
	ds_read_b64_tr_b16 v[174:175], v236 offset:35328
	ds_read_b64_tr_b16 v[176:177], v236 offset:32832
	ds_read_b64_tr_b16 v[178:179], v236 offset:35392
	s_setprio 1
	s_waitcnt lgkmcnt(14)
	v_mfma_f32_32x32x16_bf16 v[34:49], v[148:151], v[98:101], v[34:49]
	ds_read_b64_tr_b16 v[90:91], v236 offset:17536
	ds_read_b64_tr_b16 v[92:93], v236 offset:20096
	s_waitcnt lgkmcnt(14)
	v_mfma_f32_32x32x16_bf16 v[50:65], v[152:155], v[98:101], v[50:65]
	ds_read_b64_tr_b16 v[94:95], v236 offset:17600
	ds_read_b64_tr_b16 v[96:97], v236 offset:20160
	s_waitcnt lgkmcnt(14)
	v_mfma_f32_32x32x16_bf16 v[34:49], v[156:159], v[102:105], v[34:49]
	ds_read_b64_tr_b16 v[106:107], v236 offset:22656
	ds_read_b64_tr_b16 v[108:109], v236 offset:25216
	s_waitcnt lgkmcnt(14)
	v_mfma_f32_32x32x16_bf16 v[50:65], v[160:163], v[102:105], v[50:65]
	ds_read_b64_tr_b16 v[110:111], v236 offset:22720
	ds_read_b64_tr_b16 v[112:113], v236 offset:25280
	s_waitcnt lgkmcnt(14)
	v_mfma_f32_32x32x16_bf16 v[34:49], v[164:167], v[82:85], v[34:49]
	ds_read_b64_tr_b16 v[240:241], v236 offset:27776
	ds_read_b64_tr_b16 v[242:243], v236 offset:30336
	s_waitcnt lgkmcnt(14)
	v_mfma_f32_32x32x16_bf16 v[50:65], v[168:171], v[82:85], v[50:65]
	ds_read_b64_tr_b16 v[148:149], v236 offset:27840
	ds_read_b64_tr_b16 v[150:151], v236 offset:30400
	s_waitcnt lgkmcnt(14)
	v_mfma_f32_32x32x16_bf16 v[50:65], v[172:175], v[86:89], v[50:65]
	ds_read_b64_tr_b16 v[152:153], v236 offset:32896
	ds_read_b64_tr_b16 v[154:155], v236 offset:35456
	s_waitcnt lgkmcnt(14)
	v_mfma_f32_32x32x16_bf16 v[34:49], v[176:179], v[86:89], v[34:49]
	ds_read_b64_tr_b16 v[156:157], v236 offset:32960
	ds_read_b64_tr_b16 v[158:159], v236 offset:35520
	s_waitcnt lgkmcnt(14)
	v_mfma_f32_32x32x16_bf16 v[18:33], v[90:93], v[98:101], v[18:33]
	s_waitcnt lgkmcnt(12)
	v_mfma_f32_32x32x16_bf16 v[2:17], v[94:97], v[98:101], v[2:17]
	s_waitcnt lgkmcnt(10)
	v_mfma_f32_32x32x16_bf16 v[18:33], v[106:109], v[102:105], v[18:33]
	s_waitcnt lgkmcnt(8)
	v_mfma_f32_32x32x16_bf16 v[2:17], v[110:113], v[102:105], v[2:17]
	s_waitcnt lgkmcnt(6)
	v_mfma_f32_32x32x16_bf16 v[18:33], v[240:243], v[82:85], v[18:33]
	s_waitcnt lgkmcnt(4)
	v_mfma_f32_32x32x16_bf16 v[2:17], v[148:151], v[82:85], v[2:17]
	s_waitcnt lgkmcnt(2)
	v_mfma_f32_32x32x16_bf16 v[18:33], v[152:155], v[86:89], v[18:33]
	s_waitcnt lgkmcnt(0)
	v_mfma_f32_32x32x16_bf16 v[2:17], v[156:159], v[86:89], v[2:17]
	s_setprio 0
